# P1 SwiGLU epilogue hand-written with packed math like P8; GEMM prologue issues K-tile 1 loads before waiting for K-tile 0
# speedup vs baseline: 1.0448x; 1.0023x over previous
.LBB0_274:
	s_lshl_b32 s77, s7, 6
	s_lshl_b32 s20, s7, 13
	s_lshl_b32 s34, s6, 5
	s_mov_b64 s[6:7], 0x80
	s_and_b32 s78, s34, 0x60
	s_add_i32 m0, s49, 0x18000
	v_lshl_add_u64 v[6:7], v[6:7], 0, s[6:7]
	s_lshl_b32 s21, s78, 7
	global_load_lds_dwordx4 v[6:7], off
	v_lshl_add_u64 v[4:5], v[4:5], 0, s[6:7]
	s_add_i32 m0, s49, 0x1a000
	s_add_i32 s79, s49, 0x8000
	s_add_i32 s80, s49, 0xa000
	global_load_lds_dwordx4 v[4:5], off
	v_lshl_add_u64 v[0:1], v[0:1], 0, s[6:7]
	s_mov_b32 m0, s79
	s_add_u32 s18, s70, 0x40080
	global_load_lds_dwordx4 v[0:1], off
	v_lshl_add_u64 v[0:1], v[2:3], 0, s[6:7]
	s_mov_b32 m0, s80
	s_addc_u32 s19, s71, 0
	global_load_lds_dwordx4 v[0:1], off
	s_add_i32 m0, s49, 0x1c000
	v_lshl_add_u64 v[0:1], s[18:19], 0, v[132:133]
	global_load_lds_dwordx4 v[0:1], off
	v_lshl_add_u64 v[0:1], s[18:19], 0, v[128:129]
	s_add_i32 m0, s49, 0x1e000
	v_and_b32_e32 v148, 15, v9
	global_load_lds_dwordx4 v[0:1], off
	s_waitcnt vmcnt(8)
	s_barrier
	v_lshrrev_b32_e32 v0, 1, v9
	v_and_b32_e32 v0, 24, v0
	v_lshlrev_b32_e32 v1, 1, v0
	v_lshlrev_b32_e32 v2, 2, v9
	v_lshl_or_b32 v1, v148, 6, v1
	v_and_b32_e32 v2, 32, v2
	v_bitop3_b32 v3, v1, s20, v2 bitop3:0xde
	v_bitop3_b32 v149, v1, s21, v2 bitop3:0xde
	v_lshlrev_b32_e32 v1, 14, v13
	v_and_b32_e32 v1, 0xffff8000, v1
	v_lshl_add_u32 v1, v12, 11, v1
	v_and_b32_e32 v2, 1, v13
	v_lshl_or_b32 v1, v2, 6, v1
	v_lshl_add_u32 v138, v14, 1, v1
	v_lshlrev_b32_e32 v1, 14, v8
	v_and_b32_e32 v1, 0xffff8000, v1
	s_waitcnt vmcnt(6)
	s_cmpk_lt_u32 s1, 0x100
	v_lshl_add_u32 v1, v10, 11, v1
	v_and_b32_e32 v2, 1, v8
	s_cselect_b64 s[20:21], -1, 0
	v_and_or_b32 v0, s34, 32, v0
	v_lshl_or_b32 v1, v2, 6, v1
	s_add_i32 s83, 0, 0x10000
	s_add_i32 s84, 0, 0x14000
	s_sext_i32_i8 s18, s0
	s_ashr_i32 s81, s30, 31
	s_mov_b32 s82, s30
	v_mov_b32_e32 v139, v137
	v_lshl_add_u32 v140, v11, 1, v1
	v_mov_b32_e32 v141, v137
	v_mov_b64_e32 v[142:143], 0x580
	v_mov_b64_e32 v[144:145], 0x57f
	v_add_u32_e32 v150, s83, v149
	v_add_u32_e32 v151, s84, v149
	v_add_u32_e32 v152, 0, v3
	v_lshlrev_b32_e32 v146, 1, v0
	s_movk_i32 s85, 0x1000
	s_barrier
	s_waitcnt vmcnt(0)
	s_branch .LBB0_277

.LBB0_519:
	s_lshl_b32 s4, s4, 5
	s_mov_b64 s[62:63], 0x80
	s_and_b32 s7, s4, 0x60
	s_add_i32 m0, s73, 0x18000
	v_lshl_add_u64 v[6:7], v[6:7], 0, s[62:63]
	s_lshl_b32 s6, s0, 13
	s_lshl_b32 s9, s7, 7
	global_load_lds_dwordx4 v[6:7], off
	v_lshl_add_u64 v[4:5], v[4:5], 0, s[62:63]
	s_add_i32 m0, s73, 0x1a000
	s_add_i32 s81, s73, 0x8000
	s_add_i32 s97, s73, 0xa000
	global_load_lds_dwordx4 v[4:5], off
	v_lshl_add_u64 v[0:1], v[0:1], 0, s[62:63]
	s_mov_b32 m0, s81
	s_add_u32 s4, s90, 0x40080
	global_load_lds_dwordx4 v[0:1], off
	v_lshl_add_u64 v[0:1], v[2:3], 0, s[62:63]
	s_mov_b32 m0, s97
	s_addc_u32 s5, s91, 0
	global_load_lds_dwordx4 v[0:1], off
	s_add_i32 m0, s73, 0x1c000
	v_lshl_add_u64 v[0:1], s[4:5], 0, v[178:179]
	global_load_lds_dwordx4 v[0:1], off
	v_lshl_add_u64 v[0:1], s[4:5], 0, v[182:183]
	s_add_i32 m0, s73, 0x1e000
	s_cmpk_lt_u32 s3, 0x100
	global_load_lds_dwordx4 v[0:1], off
	s_waitcnt vmcnt(8)
	s_barrier
	v_bfe_u32 v1, v8, 4, 2
	v_and_b32_e32 v0, 15, v8
	v_lshlrev_b32_e32 v2, 4, v1
	v_lshl_or_b32 v222, s0, 6, v0
	v_lshl_or_b32 v0, v0, 6, v2
	v_lshlrev_b32_e32 v2, 2, v8
	v_and_b32_e32 v2, 32, v2
	v_bitop3_b32 v3, v0, s6, v2 bitop3:0xde
	v_bitop3_b32 v223, v0, s9, v2 bitop3:0xde
	v_lshlrev_b32_e32 v0, 14, v9
	v_and_b32_e32 v0, 0xffff8000, v0
	v_lshl_or_b32 v224, v1, 3, s7
	v_cmp_eq_u32_e64 s[4:5], 0, v1
	v_lshl_add_u32 v0, v10, 11, v0
	v_and_b32_e32 v1, 1, v9
	v_lshl_or_b32 v0, v1, 6, v0
	v_lshl_add_u32 v190, v11, 1, v0
	v_lshlrev_b32_e32 v0, 14, v12
	v_and_b32_e32 v0, 0xffff8000, v0
	s_waitcnt vmcnt(6)
	v_lshl_add_u32 v0, v13, 11, v0
	v_and_b32_e32 v1, 1, v12
	s_cselect_b64 s[64:65], -1, 0
	v_lshlrev_b32_e32 v184, 2, v224
	v_lshl_or_b32 v0, v1, 6, v0
	s_add_i32 s96, 0, 0x10000
	s_add_i32 s20, 0, 0x14000
	s_ashr_i32 s48, s30, 31
	s_mov_b32 s49, s30
	s_ashr_i32 s3, s2, 31
	v_lshl_add_u64 v[186:187], s[54:55], 0, v[184:185]
	v_lshl_add_u64 v[188:189], s[58:59], 0, v[184:185]
	v_mov_b32_e32 v191, v185
	v_lshl_add_u32 v192, v14, 1, v0
	v_mov_b32_e32 v193, v185
	v_mov_b64_e32 v[194:195], 0x300
	v_mov_b64_e32 v[196:197], 0x2ff
	v_add_u32_e32 v225, s96, v223
	v_add_u32_e32 v226, s20, v223
	v_add_u32_e32 v227, 0, v3
	v_mov_b32_e32 v228, 0x358637bd
	s_mov_b32 s68, 0x3e6d3388
	s_mov_b32 s70, 0x3f07dc22
	s_mov_b32 s72, 0xbf3a00e3
	s_mov_b32 s74, 0x3f35f0e3
	s_mov_b32 s76, 0xbe11a98e
	s_mov_b32 s78, 0x3e027906
	s_mov_b32 s80, 0xbf38aa3b
	v_mbcnt_hi_u32_b32 v229, -1, v248
	v_mov_b32_e32 v232, 0x3d800000
	s_mov_b32 s21, 0
	s_barrier
	s_branch .LBB0_522

.LBB0_756:
	s_lshl_b32 s8, s8, 5
	s_and_b32 s19, s8, 0x60
	s_mov_b64 s[8:9], 0x80
	s_add_i32 m0, s48, 0x18000
	v_lshl_add_u64 v[6:7], v[6:7], 0, s[8:9]
	s_lshl_b32 s11, s10, 13
	s_lshl_b32 s34, s19, 7
	global_load_lds_dwordx4 v[6:7], off
	v_lshl_add_u64 v[2:3], v[2:3], 0, s[8:9]
	s_add_i32 m0, s48, 0x1a000
	s_add_i32 s78, s48, 0x8000
	s_add_i32 s79, s48, 0xa000
	global_load_lds_dwordx4 v[2:3], off
	v_lshl_add_u64 v[0:1], v[0:1], 0, s[8:9]
	s_mov_b32 m0, s78
	s_add_u32 s12, s72, 0x40080
	global_load_lds_dwordx4 v[0:1], off
	v_lshl_add_u64 v[0:1], v[4:5], 0, s[8:9]
	s_mov_b32 m0, s79
	s_addc_u32 s13, s73, 0
	global_load_lds_dwordx4 v[0:1], off
	s_add_i32 m0, s48, 0x1c000
	v_lshl_add_u64 v[0:1], s[12:13], 0, v[150:151]
	global_load_lds_dwordx4 v[0:1], off
	v_lshl_add_u64 v[0:1], s[12:13], 0, v[154:155]
	s_add_i32 m0, s48, 0x1e000
	s_cmpk_lt_u32 s5, 0x100
	global_load_lds_dwordx4 v[0:1], off
	s_waitcnt vmcnt(8)
	s_barrier
	v_lshrrev_b32_e32 v1, 1, v8
	v_and_b32_e32 v1, 24, v1
	v_and_b32_e32 v0, 15, v8
	v_lshlrev_b32_e32 v2, 1, v1
	v_lshl_or_b32 v172, s10, 6, v0
	v_lshl_or_b32 v0, v0, 6, v2
	v_lshlrev_b32_e32 v2, 2, v8
	v_and_b32_e32 v2, 32, v2
	v_bitop3_b32 v3, v0, s11, v2 bitop3:0xde
	v_bitop3_b32 v173, v0, s34, v2 bitop3:0xde
	v_lshlrev_b32_e32 v0, 14, v9
	v_and_b32_e32 v0, 0xffff8000, v0
	v_or_b32_e32 v174, s19, v1
	v_lshl_add_u32 v0, v10, 11, v0
	v_and_b32_e32 v1, 1, v9
	v_lshl_or_b32 v0, v1, 6, v0
	v_lshl_add_u32 v156, v11, 1, v0
	v_lshlrev_b32_e32 v0, 14, v12
	v_and_b32_e32 v0, 0xffff8000, v0
	s_waitcnt vmcnt(6)
	v_lshl_add_u32 v0, v13, 11, v0
	v_and_b32_e32 v1, 1, v12
	s_cselect_b64 s[10:11], -1, 0
	v_lshl_or_b32 v0, v1, 6, v0
	s_add_i32 s82, 0, 0x10000
	s_add_i32 s83, 0, 0x14000
	s_sext_i32_i8 s18, s4
	s_ashr_i32 s80, s30, 31
	s_mov_b32 s81, s30
	v_mov_b32_e32 v157, v151
	v_lshl_add_u32 v158, v14, 1, v0
	v_mov_b32_e32 v159, v151
	v_mov_b64_e32 v[160:161], 0x100
	v_mov_b64_e32 v[162:163], 0xff
	v_add_u32_e32 v175, s82, v173
	v_add_u32_e32 v176, s83, v173
	v_add_u32_e32 v177, 0, v3
	s_mov_b32 s84, 0x40000
	s_mov_b64 s[12:13], 0x48000
	s_mov_b32 s85, 0x48000
	s_mov_b64 s[38:39], 0x50000
	s_mov_b32 s86, 0x50000
	s_mov_b64 s[40:41], 0x58000
	s_mov_b32 s87, 0x58000
	s_barrier
	s_branch .LBB0_759

.LBB0_778:
	s_lshl_b32 s5, s5, 5
	s_mov_b64 s[42:43], 0x80
	s_and_b32 s5, s5, 0x60
	s_add_i32 m0, s21, 0x18000
	v_lshl_add_u64 v[6:7], v[6:7], 0, s[42:43]
	s_lshl_b32 s1, s4, 13
	s_lshl_b32 s7, s5, 7
	global_load_lds_dwordx4 v[6:7], off
	v_lshl_add_u64 v[4:5], v[4:5], 0, s[42:43]
	s_add_i32 m0, s21, 0x1a000
	s_add_i32 s65, s21, 0x8000
	s_add_i32 s69, s21, 0xa000
	global_load_lds_dwordx4 v[4:5], off
	v_lshl_add_u64 v[0:1], v[0:1], 0, s[42:43]
	s_mov_b32 m0, s65
	s_add_u32 s18, s12, 0x40080
	global_load_lds_dwordx4 v[0:1], off
	v_lshl_add_u64 v[0:1], v[2:3], 0, s[42:43]
	s_mov_b32 m0, s69
	s_addc_u32 s19, s13, 0
	global_load_lds_dwordx4 v[0:1], off
	s_add_i32 m0, s21, 0x1c000
	v_lshl_add_u64 v[0:1], s[18:19], 0, v[178:179]
	global_load_lds_dwordx4 v[0:1], off
	v_lshl_add_u64 v[0:1], s[18:19], 0, v[182:183]
	s_add_i32 m0, s21, 0x1e000
	s_cmpk_lt_u32 s6, 0x100
	global_load_lds_dwordx4 v[0:1], off
	s_waitcnt vmcnt(8)
	s_barrier
	v_bfe_u32 v1, v8, 4, 2
	v_and_b32_e32 v0, 15, v8
	v_lshlrev_b32_e32 v2, 4, v1
	v_lshl_or_b32 v222, s4, 6, v0
	v_lshl_or_b32 v0, v0, 6, v2
	v_lshlrev_b32_e32 v2, 2, v8
	v_and_b32_e32 v2, 32, v2
	v_bitop3_b32 v3, v0, s1, v2 bitop3:0xde
	v_bitop3_b32 v223, v0, s7, v2 bitop3:0xde
	v_lshlrev_b32_e32 v0, 14, v9
	v_and_b32_e32 v0, 0xffff8000, v0
	v_lshl_or_b32 v224, v1, 3, s5
	v_cmp_eq_u32_e64 s[4:5], 0, v1
	v_lshl_add_u32 v0, v10, 11, v0
	v_and_b32_e32 v1, 1, v9
	v_lshl_or_b32 v0, v1, 6, v0
	v_lshl_add_u32 v190, v11, 1, v0
	v_lshlrev_b32_e32 v0, 14, v12
	v_and_b32_e32 v0, 0xffff8000, v0
	s_waitcnt vmcnt(6)
	v_lshlrev_b32_e32 v184, 2, v224
	v_lshl_add_u32 v0, v13, 11, v0
	v_and_b32_e32 v1, 1, v12
	s_cselect_b64 s[60:61], -1, 0
	v_lshl_add_u64 v[188:189], s[58:59], 0, v[184:185]
	v_lshl_or_b32 v0, v1, 6, v0
	s_add_i32 s59, 0, 0x10000
	s_add_i32 s87, 0, 0x14000
	s_ashr_i32 s71, s30, 31
	s_mov_b32 s73, s30
	s_ashr_i32 s86, s2, 31
	v_lshl_add_u64 v[186:187], s[54:55], 0, v[184:185]
	v_mov_b32_e32 v191, v185
	v_lshl_add_u32 v192, v14, 1, v0
	v_mov_b32_e32 v193, v185
	v_mov_b64_e32 v[194:195], 0x500
	v_mov_b64_e32 v[196:197], 0x4ff
	s_movk_i32 s55, 0xa1
	v_add_u32_e32 v225, s59, v223
	v_add_u32_e32 v226, s87, v223
	v_add_u32_e32 v227, 0, v3
	s_movk_i32 s88, 0x1400
	s_mov_b32 s89, 0xba80000
	v_mov_b32_e32 v228, 0x358637bd
	s_mov_b32 s54, 0x3e6d3388
	s_mov_b32 s58, 0x3f07dc22
	s_mov_b32 s62, 0xbf3a00e3
	s_mov_b32 s64, 0x3f35f0e3
	s_mov_b32 s68, 0xbe11a98e
	s_mov_b32 s70, 0x3e027906
	s_mov_b32 s72, 0xbf38aa3b
	v_mbcnt_hi_u32_b32 v229, -1, v248
	v_mov_b32_e32 v232, 0x3d800000
	s_mov_b32 s90, 0
	s_barrier
	s_branch .LBB0_781

.LBB0_1165:
	s_lshl_b32 s6, s6, 5
	s_and_b32 s12, s6, 0x60
	s_mov_b64 s[6:7], 0x80
	s_add_i32 m0, s39, 0x18000
	v_lshl_add_u64 v[6:7], v[6:7], 0, s[6:7]
	s_lshl_b32 s9, s8, 13
	s_lshl_b32 s13, s12, 7
	global_load_lds_dwordx4 v[6:7], off
	v_lshl_add_u64 v[4:5], v[4:5], 0, s[6:7]
	s_add_i32 m0, s39, 0x1a000
	s_add_i32 s54, s39, 0x8000
	s_add_i32 s55, s39, 0xa000
	global_load_lds_dwordx4 v[4:5], off
	v_lshl_add_u64 v[0:1], v[0:1], 0, s[6:7]
	s_mov_b32 m0, s54
	s_add_u32 s10, s42, 0x40080
	global_load_lds_dwordx4 v[0:1], off
	v_lshl_add_u64 v[0:1], v[2:3], 0, s[6:7]
	s_mov_b32 m0, s55
	s_addc_u32 s11, s43, 0
	global_load_lds_dwordx4 v[0:1], off
	s_add_i32 m0, s39, 0x1c000
	v_lshl_add_u64 v[0:1], s[10:11], 0, v[174:175]
	global_load_lds_dwordx4 v[0:1], off
	v_lshl_add_u64 v[0:1], s[10:11], 0, v[178:179]
	s_add_i32 m0, s39, 0x1e000
	s_cmpk_lt_u32 s5, 0x100
	global_load_lds_dwordx4 v[0:1], off
	s_waitcnt vmcnt(8)
	s_barrier
	v_lshrrev_b32_e32 v1, 1, v8
	v_and_b32_e32 v1, 24, v1
	v_and_b32_e32 v0, 15, v8
	v_lshlrev_b32_e32 v2, 1, v1
	v_lshl_or_b32 v198, s8, 6, v0
	v_lshl_or_b32 v0, v0, 6, v2
	v_lshlrev_b32_e32 v2, 2, v8
	v_and_b32_e32 v2, 32, v2
	v_bitop3_b32 v3, v0, s9, v2 bitop3:0xde
	v_bitop3_b32 v199, v0, s13, v2 bitop3:0xde
	v_lshlrev_b32_e32 v0, 14, v9
	v_and_b32_e32 v0, 0xffff8000, v0
	v_or_b32_e32 v200, s12, v1
	v_lshl_add_u32 v0, v10, 11, v0
	v_and_b32_e32 v1, 1, v9
	v_lshl_or_b32 v0, v1, 6, v0
	v_lshl_add_u32 v180, v11, 1, v0
	v_lshlrev_b32_e32 v0, 14, v12
	v_and_b32_e32 v0, 0xffff8000, v0
	s_waitcnt vmcnt(6)
	v_lshl_add_u32 v0, v13, 11, v0
	v_and_b32_e32 v1, 1, v12
	s_cselect_b64 s[8:9], -1, 0
	v_lshl_or_b32 v0, v1, 6, v0
	s_add_i32 s58, 0, 0x10000
	s_add_i32 s59, 0, 0x14000
	s_sext_i32_i8 s18, s4
	s_ashr_i32 s56, s30, 31
	s_mov_b32 s57, s30
	v_mov_b32_e32 v181, v175
	v_lshl_add_u32 v182, v14, 1, v0
	v_mov_b32_e32 v183, v175
	v_mov_b64_e32 v[184:185], 0x100
	v_mov_b64_e32 v[186:187], 0xff
	v_add_u32_e32 v201, s58, v199
	v_add_u32_e32 v202, s59, v199
	v_add_u32_e32 v203, 0, v3
	s_barrier
	s_branch .LBB0_1168

.LBB0_1331:
	s_lshl_b32 s53, s9, 6
	s_lshl_b32 s12, s9, 13
	s_lshl_b32 s13, s8, 5
	s_mov_b64 s[8:9], 0x80
	s_and_b32 s54, s13, 0x60
	s_add_i32 m0, s39, 0x18000
	v_lshl_add_u64 v[6:7], v[6:7], 0, s[8:9]
	s_lshl_b32 s14, s54, 7
	global_load_lds_dwordx4 v[6:7], off
	v_lshl_add_u64 v[4:5], v[4:5], 0, s[8:9]
	s_add_i32 m0, s39, 0x1a000
	s_add_i32 s55, s39, 0x8000
	s_add_i32 s56, s39, 0xa000
	global_load_lds_dwordx4 v[4:5], off
	v_lshl_add_u64 v[0:1], v[0:1], 0, s[8:9]
	s_mov_b32 m0, s55
	s_add_u32 s10, s42, 0x40080
	global_load_lds_dwordx4 v[0:1], off
	v_lshl_add_u64 v[0:1], v[2:3], 0, s[8:9]
	s_mov_b32 m0, s56
	s_addc_u32 s11, s43, 0
	global_load_lds_dwordx4 v[0:1], off
	s_add_i32 m0, s39, 0x1c000
	v_lshl_add_u64 v[0:1], s[10:11], 0, v[132:133]
	global_load_lds_dwordx4 v[0:1], off
	v_lshl_add_u64 v[0:1], s[10:11], 0, v[128:129]
	s_add_i32 m0, s39, 0x1e000
	v_and_b32_e32 v148, 15, v9
	global_load_lds_dwordx4 v[0:1], off
	s_waitcnt vmcnt(8)
	s_barrier
	v_lshrrev_b32_e32 v0, 1, v9
	v_and_b32_e32 v0, 24, v0
	v_lshlrev_b32_e32 v1, 1, v0
	v_lshlrev_b32_e32 v2, 2, v9
	v_lshl_or_b32 v1, v148, 6, v1
	v_and_b32_e32 v2, 32, v2
	v_bitop3_b32 v3, v1, s12, v2 bitop3:0xde
	v_bitop3_b32 v149, v1, s14, v2 bitop3:0xde
	v_lshlrev_b32_e32 v1, 14, v13
	v_and_b32_e32 v1, 0xffff8000, v1
	v_lshl_add_u32 v1, v12, 11, v1
	v_and_b32_e32 v2, 1, v13
	v_lshl_or_b32 v1, v2, 6, v1
	v_lshl_add_u32 v138, v14, 1, v1
	v_lshlrev_b32_e32 v1, 14, v8
	v_and_b32_e32 v1, 0xffff8000, v1
	s_waitcnt vmcnt(6)
	s_cmpk_lt_u32 s5, 0x100
	v_lshl_add_u32 v1, v10, 11, v1
	v_and_b32_e32 v2, 1, v8
	s_cselect_b64 s[10:11], -1, 0
	v_and_or_b32 v0, s13, 32, v0
	v_lshl_or_b32 v1, v2, 6, v1
	s_add_i32 s59, 0, 0x10000
	s_add_i32 s60, 0, 0x14000
	s_sext_i32_i8 s18, s4
	s_ashr_i32 s57, s30, 31
	s_mov_b32 s58, s30
	v_mov_b32_e32 v139, v137
	v_lshl_add_u32 v140, v11, 1, v1
	v_mov_b32_e32 v141, v137
	v_mov_b64_e32 v[142:143], 0x580
	v_mov_b64_e32 v[144:145], 0x57f
	v_add_u32_e32 v150, s59, v149
	v_add_u32_e32 v151, s60, v149
	v_add_u32_e32 v152, 0, v3
	v_mov_b32_e32 v153, 0x358637bd
	v_lshlrev_b32_e32 v146, 1, v0
	s_movk_i32 s61, 0x1000
	s_barrier
	s_branch .LBB0_1334
